# epiin: hand-written lean in-proj epilogue for plain tiles (pn 4-7, 9-17) in front of compiler EpiIn, on top of v41 set
# baseline (speedup 1.0000x reference)
; #define GAS __attribute__((address_space(1)))
; __device__ __forceinline__ unsigned cvt_pk_bf16(float lo, float hi) { unsigned r; asm volatile("v_cvt_pk_bf16_f32 %0, %1, %2" : "=v"(r) : "v"(lo), "v"(hi)); return r; }
;     __device__ __forceinline__ void operator()(const f32x4 (&acc)[2][2][4][2], const Unit& u, int wr, int wc, int fr, int fq, const PG8_LAS float* tab) const {
;     ...
;                 const int row = u.pm * BM + ai * HALF + wr * 64 + m * 16 + fr;
;                 const float rs = rsqrtf(tab[ai * HALF + wr * 64 + m * 16 + fr] * (1.0f / 2048.0f) + 1e-6f);
;                 const int pos = row < 16384 ? (row & 8191) : (row - 16384);
;                 GAS bf16_t* rowp = (GAS bf16_t*)P + (size_t)row * 5120;
;     ...
; #pragma unroll
;                 for (int bj = 0; bj < 2; ++bj) {
;                     const int col0 = pn * BM + bj * HALF + wc * 32 + 8 * fq;
;                     f32x4 v0 = acc[ai][bj][m][0] * rs, v1 = acc[ai][bj][m][1] * rs;
;                     if (is_rope) {
;                         const GAS f32x4* rp = (const GAS f32x4*)((const GAS f32x2*)rope + (size_t)pos * 32 + ((col0 & 63) >> 1));
;                         const f32x4 cs0 = rp[0], cs1 = rp[1];
;                         f32x4 o0, o1;
;                         o0[0] = v0[0] * cs0[0] - v0[1] * cs0[1]; o0[1] = v0[1] * cs0[0] + v0[0] * cs0[1];
;                         o0[2] = v0[2] * cs0[2] - v0[3] * cs0[3]; o0[3] = v0[3] * cs0[2] + v0[2] * cs0[3];
;                         o1[0] = v1[0] * cs1[0] - v1[1] * cs1[1]; o1[1] = v1[1] * cs1[0] + v1[0] * cs1[1];
;                         o1[2] = v1[2] * cs1[2] - v1[3] * cs1[3]; o1[3] = v1[3] * cs1[2] + v1[2] * cs1[3];
;                         v0 = o0 * qs; v1 = o1 * qs;
;                     }
;                     {
;                         u32x4 w; w.x = cvt_pk_bf16(v0[0], v0[1]); w.y = cvt_pk_bf16(v0[2], v0[3]); w.z = cvt_pk_bf16(v1[0], v1[1]); w.w = cvt_pk_bf16(v1[2], v1[3]);
;                         *(GAS u32x4*)(rowp + col0) = w;
;                     }
.LBB0_348:
	s_cmp_lt_i32 s0, 4
	s_cbranch_scc1 .Lei_compiler
	s_cmp_eq_u32 s0, 8
	s_cbranch_scc1 .Lei_compiler
	s_cmp_gt_i32 s0, 17
	s_cbranch_scc1 .Lei_compiler
	s_and_b32 s4, s3, 1
	s_lshl_b32 s4, s4, 10
	v_add_u32_e32 v171, s4, v172
	ds_read_b32 v154, v171 offset:0
	ds_read_b32 v156, v171 offset:64
	ds_read_b32 v158, v171 offset:128
	ds_read_b32 v160, v171 offset:192
	ds_read_b32 v155, v171 offset:512
	ds_read_b32 v157, v171 offset:576
	ds_read_b32 v159, v171 offset:640
	ds_read_b32 v161, v171 offset:704
	s_mul_i32 s4, s1, 0x280000
	s_lshl_b32 s5, s0, 9
	s_add_u32 s4, s4, s5
	s_add_u32 s6, s86, s4
	s_addc_u32 s7, s87, 0
	v_mul_u32_u24_e32 v170, 0x2800, v1
	v_lshl_add_u32 v170, v173, 1, v170
	s_waitcnt lgkmcnt(0)
	v_fmamk_f32 v154, v154, 0x3a000000, v236
	v_fmamk_f32 v156, v156, 0x3a000000, v236
	v_fmamk_f32 v158, v158, 0x3a000000, v236
	v_fmamk_f32 v160, v160, 0x3a000000, v236
	v_fmamk_f32 v155, v155, 0x3a000000, v236
	v_fmamk_f32 v157, v157, 0x3a000000, v236
	v_fmamk_f32 v159, v159, 0x3a000000, v236
	v_fmamk_f32 v161, v161, 0x3a000000, v236
	v_rsq_f32_e32 v154, v154
	v_rsq_f32_e32 v156, v156
	v_rsq_f32_e32 v158, v158
	v_rsq_f32_e32 v160, v160
	v_rsq_f32_e32 v155, v155
	v_rsq_f32_e32 v157, v157
	v_rsq_f32_e32 v159, v159
	v_rsq_f32_e32 v161, v161
	v_pk_mul_f32 v[126:127], v[126:127], v[154:155] op_sel_hi:[1,0]
	v_pk_mul_f32 v[128:129], v[128:129], v[154:155] op_sel_hi:[1,0]
	v_pk_mul_f32 v[122:123], v[122:123], v[154:155] op_sel_hi:[1,0]
	v_pk_mul_f32 v[124:125], v[124:125], v[154:155] op_sel_hi:[1,0]
	v_cvt_pk_bf16_f32 v162, v126, v127
	v_cvt_pk_bf16_f32 v163, v128, v129
	v_cvt_pk_bf16_f32 v164, v122, v123
	v_cvt_pk_bf16_f32 v165, v124, v125
	s_mov_b64 s[10:11], s[6:7]
	global_store_dwordx4 v170, v[162:165], s[10:11] offset:0
	v_pk_mul_f32 v[118:119], v[118:119], v[154:155] op_sel_hi:[1,0]
	v_pk_mul_f32 v[120:121], v[120:121], v[154:155] op_sel_hi:[1,0]
	v_pk_mul_f32 v[114:115], v[114:115], v[154:155] op_sel_hi:[1,0]
	v_pk_mul_f32 v[116:117], v[116:117], v[154:155] op_sel_hi:[1,0]
	v_cvt_pk_bf16_f32 v166, v118, v119
	v_cvt_pk_bf16_f32 v167, v120, v121
	v_cvt_pk_bf16_f32 v168, v114, v115
	v_cvt_pk_bf16_f32 v169, v116, v117
	global_store_dwordx4 v170, v[166:169], s[10:11] offset:256
	v_pk_mul_f32 v[110:111], v[110:111], v[156:157] op_sel_hi:[1,0]
	v_pk_mul_f32 v[112:113], v[112:113], v[156:157] op_sel_hi:[1,0]
	v_pk_mul_f32 v[106:107], v[106:107], v[156:157] op_sel_hi:[1,0]
	v_pk_mul_f32 v[108:109], v[108:109], v[156:157] op_sel_hi:[1,0]
	v_cvt_pk_bf16_f32 v162, v110, v111
	v_cvt_pk_bf16_f32 v163, v112, v113
	v_cvt_pk_bf16_f32 v164, v106, v107
	v_cvt_pk_bf16_f32 v165, v108, v109
	s_add_u32 s10, s6, 0x28000
	s_addc_u32 s11, s7, 0
	global_store_dwordx4 v170, v[162:165], s[10:11] offset:0
	v_pk_mul_f32 v[102:103], v[102:103], v[156:157] op_sel_hi:[1,0]
	v_pk_mul_f32 v[104:105], v[104:105], v[156:157] op_sel_hi:[1,0]
	v_pk_mul_f32 v[98:99], v[98:99], v[156:157] op_sel_hi:[1,0]
	v_pk_mul_f32 v[100:101], v[100:101], v[156:157] op_sel_hi:[1,0]
	v_cvt_pk_bf16_f32 v166, v102, v103
	v_cvt_pk_bf16_f32 v167, v104, v105
	v_cvt_pk_bf16_f32 v168, v98, v99
	v_cvt_pk_bf16_f32 v169, v100, v101
	global_store_dwordx4 v170, v[166:169], s[10:11] offset:256
	v_pk_mul_f32 v[94:95], v[94:95], v[158:159] op_sel_hi:[1,0]
	v_pk_mul_f32 v[96:97], v[96:97], v[158:159] op_sel_hi:[1,0]
	v_pk_mul_f32 v[90:91], v[90:91], v[158:159] op_sel_hi:[1,0]
	v_pk_mul_f32 v[92:93], v[92:93], v[158:159] op_sel_hi:[1,0]
	v_cvt_pk_bf16_f32 v162, v94, v95
	v_cvt_pk_bf16_f32 v163, v96, v97
	v_cvt_pk_bf16_f32 v164, v90, v91
	v_cvt_pk_bf16_f32 v165, v92, v93
	s_add_u32 s10, s6, 0x50000
	s_addc_u32 s11, s7, 0
	global_store_dwordx4 v170, v[162:165], s[10:11] offset:0
	v_pk_mul_f32 v[86:87], v[86:87], v[158:159] op_sel_hi:[1,0]
	v_pk_mul_f32 v[88:89], v[88:89], v[158:159] op_sel_hi:[1,0]
	v_pk_mul_f32 v[82:83], v[82:83], v[158:159] op_sel_hi:[1,0]
	v_pk_mul_f32 v[84:85], v[84:85], v[158:159] op_sel_hi:[1,0]
	v_cvt_pk_bf16_f32 v166, v86, v87
	v_cvt_pk_bf16_f32 v167, v88, v89
	v_cvt_pk_bf16_f32 v168, v82, v83
	v_cvt_pk_bf16_f32 v169, v84, v85
	global_store_dwordx4 v170, v[166:169], s[10:11] offset:256
	v_pk_mul_f32 v[78:79], v[78:79], v[160:161] op_sel_hi:[1,0]
	v_pk_mul_f32 v[80:81], v[80:81], v[160:161] op_sel_hi:[1,0]
	v_pk_mul_f32 v[74:75], v[74:75], v[160:161] op_sel_hi:[1,0]
	v_pk_mul_f32 v[76:77], v[76:77], v[160:161] op_sel_hi:[1,0]
	v_cvt_pk_bf16_f32 v162, v78, v79
	v_cvt_pk_bf16_f32 v163, v80, v81
; #define GAS __attribute__((address_space(1)))
; __device__ __forceinline__ unsigned cvt_pk_bf16(float lo, float hi) { unsigned r; asm volatile("v_cvt_pk_bf16_f32 %0, %1, %2" : "=v"(r) : "v"(lo), "v"(hi)); return r; }
;     __device__ __forceinline__ void operator()(const f32x4 (&acc)[2][2][4][2], const Unit& u, int wr, int wc, int fr, int fq, const PG8_LAS float* tab) const {
;     ...
; #pragma unroll
;                 for (int bj = 0; bj < 2; ++bj) {
;                     const int col0 = pn * BM + bj * HALF + wc * 32 + 8 * fq;
;                     f32x4 v0 = acc[ai][bj][m][0] * rs, v1 = acc[ai][bj][m][1] * rs;
;                     if (is_rope) {
;                         const GAS f32x4* rp = (const GAS f32x4*)((const GAS f32x2*)rope + (size_t)pos * 32 + ((col0 & 63) >> 1));
;                         const f32x4 cs0 = rp[0], cs1 = rp[1];
;                         f32x4 o0, o1;
;                         o0[0] = v0[0] * cs0[0] - v0[1] * cs0[1]; o0[1] = v0[1] * cs0[0] + v0[0] * cs0[1];
;                         o0[2] = v0[2] * cs0[2] - v0[3] * cs0[3]; o0[3] = v0[3] * cs0[2] + v0[2] * cs0[3];
;                         o1[0] = v1[0] * cs1[0] - v1[1] * cs1[1]; o1[1] = v1[1] * cs1[0] + v1[0] * cs1[1];
;                         o1[2] = v1[2] * cs1[2] - v1[3] * cs1[3]; o1[3] = v1[3] * cs1[2] + v1[2] * cs1[3];
;                         v0 = o0 * qs; v1 = o1 * qs;
;                     }
;                     {
;                         u32x4 w; w.x = cvt_pk_bf16(v0[0], v0[1]); w.y = cvt_pk_bf16(v0[2], v0[3]); w.z = cvt_pk_bf16(v1[0], v1[1]); w.w = cvt_pk_bf16(v1[2], v1[3]);
;                         *(GAS u32x4*)(rowp + col0) = w;
;                     }
	v_cvt_pk_bf16_f32 v164, v74, v75
	v_cvt_pk_bf16_f32 v165, v76, v77
	s_add_u32 s10, s6, 0x78000
	s_addc_u32 s11, s7, 0
	global_store_dwordx4 v170, v[162:165], s[10:11] offset:0
	v_pk_mul_f32 v[70:71], v[70:71], v[160:161] op_sel_hi:[1,0]
	v_pk_mul_f32 v[72:73], v[72:73], v[160:161] op_sel_hi:[1,0]
	v_pk_mul_f32 v[66:67], v[66:67], v[160:161] op_sel_hi:[1,0]
	v_pk_mul_f32 v[68:69], v[68:69], v[160:161] op_sel_hi:[1,0]
	v_cvt_pk_bf16_f32 v166, v70, v71
	v_cvt_pk_bf16_f32 v167, v72, v73
	v_cvt_pk_bf16_f32 v168, v66, v67
	v_cvt_pk_bf16_f32 v169, v68, v69
	global_store_dwordx4 v170, v[166:169], s[10:11] offset:256
	v_mov_b32_e32 v154, v155
	v_mov_b32_e32 v156, v157
	v_mov_b32_e32 v158, v159
	v_mov_b32_e32 v160, v161
	v_pk_mul_f32 v[62:63], v[62:63], v[154:155] op_sel_hi:[1,0]
	v_pk_mul_f32 v[64:65], v[64:65], v[154:155] op_sel_hi:[1,0]
	v_pk_mul_f32 v[58:59], v[58:59], v[154:155] op_sel_hi:[1,0]
	v_pk_mul_f32 v[60:61], v[60:61], v[154:155] op_sel_hi:[1,0]
	v_cvt_pk_bf16_f32 v162, v62, v63
	v_cvt_pk_bf16_f32 v163, v64, v65
	v_cvt_pk_bf16_f32 v164, v58, v59
	v_cvt_pk_bf16_f32 v165, v60, v61
	s_add_u32 s10, s6, 0x140000
	s_addc_u32 s11, s7, 0
	global_store_dwordx4 v170, v[162:165], s[10:11] offset:0
	v_pk_mul_f32 v[54:55], v[54:55], v[154:155] op_sel_hi:[1,0]
	v_pk_mul_f32 v[56:57], v[56:57], v[154:155] op_sel_hi:[1,0]
	v_pk_mul_f32 v[50:51], v[50:51], v[154:155] op_sel_hi:[1,0]
	v_pk_mul_f32 v[52:53], v[52:53], v[154:155] op_sel_hi:[1,0]
	v_cvt_pk_bf16_f32 v166, v54, v55
	v_cvt_pk_bf16_f32 v167, v56, v57
	v_cvt_pk_bf16_f32 v168, v50, v51
	v_cvt_pk_bf16_f32 v169, v52, v53
	global_store_dwordx4 v170, v[166:169], s[10:11] offset:256
	v_pk_mul_f32 v[46:47], v[46:47], v[156:157] op_sel_hi:[1,0]
	v_pk_mul_f32 v[48:49], v[48:49], v[156:157] op_sel_hi:[1,0]
	v_pk_mul_f32 v[42:43], v[42:43], v[156:157] op_sel_hi:[1,0]
	v_pk_mul_f32 v[44:45], v[44:45], v[156:157] op_sel_hi:[1,0]
	v_cvt_pk_bf16_f32 v162, v46, v47
	v_cvt_pk_bf16_f32 v163, v48, v49
	v_cvt_pk_bf16_f32 v164, v42, v43
	v_cvt_pk_bf16_f32 v165, v44, v45
	s_add_u32 s10, s6, 0x168000
	s_addc_u32 s11, s7, 0
	global_store_dwordx4 v170, v[162:165], s[10:11] offset:0
	v_pk_mul_f32 v[38:39], v[38:39], v[156:157] op_sel_hi:[1,0]
	v_pk_mul_f32 v[40:41], v[40:41], v[156:157] op_sel_hi:[1,0]
	v_pk_mul_f32 v[34:35], v[34:35], v[156:157] op_sel_hi:[1,0]
	v_pk_mul_f32 v[36:37], v[36:37], v[156:157] op_sel_hi:[1,0]
	v_cvt_pk_bf16_f32 v166, v38, v39
	v_cvt_pk_bf16_f32 v167, v40, v41
	v_cvt_pk_bf16_f32 v168, v34, v35
	v_cvt_pk_bf16_f32 v169, v36, v37
	global_store_dwordx4 v170, v[166:169], s[10:11] offset:256
	v_pk_mul_f32 v[30:31], v[30:31], v[158:159] op_sel_hi:[1,0]
	v_pk_mul_f32 v[32:33], v[32:33], v[158:159] op_sel_hi:[1,0]
	v_pk_mul_f32 v[26:27], v[26:27], v[158:159] op_sel_hi:[1,0]
	v_pk_mul_f32 v[28:29], v[28:29], v[158:159] op_sel_hi:[1,0]
	v_cvt_pk_bf16_f32 v162, v30, v31
	v_cvt_pk_bf16_f32 v163, v32, v33
	v_cvt_pk_bf16_f32 v164, v26, v27
	v_cvt_pk_bf16_f32 v165, v28, v29
	s_add_u32 s10, s6, 0x190000
	s_addc_u32 s11, s7, 0
	global_store_dwordx4 v170, v[162:165], s[10:11] offset:0
	v_pk_mul_f32 v[22:23], v[22:23], v[158:159] op_sel_hi:[1,0]
	v_pk_mul_f32 v[24:25], v[24:25], v[158:159] op_sel_hi:[1,0]
	v_pk_mul_f32 v[18:19], v[18:19], v[158:159] op_sel_hi:[1,0]
	v_pk_mul_f32 v[20:21], v[20:21], v[158:159] op_sel_hi:[1,0]
	v_cvt_pk_bf16_f32 v166, v22, v23
	v_cvt_pk_bf16_f32 v167, v24, v25
	v_cvt_pk_bf16_f32 v168, v18, v19
	v_cvt_pk_bf16_f32 v169, v20, v21
	global_store_dwordx4 v170, v[166:169], s[10:11] offset:256
	v_pk_mul_f32 v[14:15], v[14:15], v[160:161] op_sel_hi:[1,0]
	v_pk_mul_f32 v[16:17], v[16:17], v[160:161] op_sel_hi:[1,0]
	v_pk_mul_f32 v[10:11], v[10:11], v[160:161] op_sel_hi:[1,0]
	v_pk_mul_f32 v[12:13], v[12:13], v[160:161] op_sel_hi:[1,0]
	v_cvt_pk_bf16_f32 v162, v14, v15
	v_cvt_pk_bf16_f32 v163, v16, v17
	v_cvt_pk_bf16_f32 v164, v10, v11
	v_cvt_pk_bf16_f32 v165, v12, v13
	s_add_u32 s10, s6, 0x1b8000
	s_addc_u32 s11, s7, 0
	global_store_dwordx4 v170, v[162:165], s[10:11] offset:0
	v_pk_mul_f32 v[6:7], v[6:7], v[160:161] op_sel_hi:[1,0]
	v_pk_mul_f32 v[8:9], v[8:9], v[160:161] op_sel_hi:[1,0]
	v_pk_mul_f32 v[2:3], v[2:3], v[160:161] op_sel_hi:[1,0]
	v_pk_mul_f32 v[4:5], v[4:5], v[160:161] op_sel_hi:[1,0]
	v_cvt_pk_bf16_f32 v166, v6, v7
	v_cvt_pk_bf16_f32 v167, v8, v9
	v_cvt_pk_bf16_f32 v168, v2, v3
	v_cvt_pk_bf16_f32 v169, v4, v5
	global_store_dwordx4 v170, v[166:169], s[10:11] offset:256
	s_branch .LBB0_406
